# XCD-local barrier with one counter: waiters poll the arrival word until it reaches (gen+1)*nloc; the separate release word and its extra atomic round trip removed
# baseline (speedup 1.0000x reference)
.LBB0_576:
	s_or_b64 exec, exec, s[10:11]
	s_waitcnt vmcnt(0)
	v_readfirstlane_b32 s3, v3
	v_readlane_b32 s8, v254, 0
	v_readlane_b32 s9, v254, 1
	v_add3_u32 v1, s3, v1, 1
	v_readlane_b32 s3, v253, 5
	s_mov_b64 s[10:11], 0
	s_nop 0
	v_mul_lo_u32 v0, v0, s3
	v_mov_b32_e32 v4, v0
	v_cmp_ne_u32_e32 vcc, v1, v0
	v_mov_b64_e32 v[0:1], s[8:9]
	s_and_saveexec_b64 s[8:9], vcc
	s_cbranch_execz .LBB0_619
	v_readlane_b32 s10, v253, 62
	v_readlane_b32 s11, v253, 63
	s_nop 4
	global_load_dword v0, v129, s[10:11] sc1
	s_mov_b64 s[10:11], 0
	s_waitcnt vmcnt(0)
	v_cmp_lt_u32_e32 vcc, v0, v4
	s_cbranch_vccz .LBB0_618
	s_mov_b32 s3, 1
	s_branch .LBB0_580

.LBB0_582:
	v_readlane_b32 s10, v253, 62
	v_readlane_b32 s11, v253, 63
	s_add_i32 s3, s3, 1
	s_mov_b64 s[12:13], -1
	s_nop 2
	global_load_dword v0, v129, s[10:11] sc1
	s_waitcnt vmcnt(0)
	v_cmp_ge_u32_e64 s[10:11], v0, v4
	s_branch .LBB0_579
